# grid syncs 2..14 use a monotonic-counter barrier in d_ws (zeroed in phase 0, first sync stays cooperative-groups) instead of cg::grid.sync
# speedup vs baseline: 1.0064x; 1.0062x over previous
; DI int my_tid() { int t = threadIdx.x; asm volatile("" : "+v"(t)); return t; }
; DI void phase_prep(PRef p) {
;   const int tid0 = my_tid();
;   const int gtid = blockIdx.x * 512 + tid0, gthreads = gridDim.x * 512;
;   char* ws = p.ws;
;   for (int j = 0; j < 2; j++) {
;     conv_w(p.in[5] + (size_t)j * 1024 * 1952, 1024, 1952, 2048, p.in[4] + (2 * j) * 1024, (short*)(ws + OFF_WIA) + (size_t)j * 2048 * 1024, 1, gtid, gthreads);
;     conv_w(p.in[12] + (size_t)j * 1024 * 2816, 1024, 2816, 2816, p.in[4] + (2 * j + 1) * 1024, (short*)(ws + OFF_WIB) + (size_t)j * 2816 * 1024, 0, gtid, gthreads);
;     conv_w(p.in[8] + (size_t)j * 384 * 1152, 384, 1152, 1152, p.in[6] + j * 384, (short*)(ws + OFF_WUQ) + (size_t)j * 1152 * 384, 0, gtid, gthreads);
;     conv_w(p.in[9] + (size_t)j * 256 * 1536, 256, 1536, 1536, p.in[7] + j * 256, (short*)(ws + OFF_WUKV) + (size_t)j * 1536 * 256, 0, gtid, gthreads);
;   }
.LBB0_845:
	v_mov_b32_e32 v8, v196
	s_waitcnt lgkmcnt(0)
	s_load_dwordx8 s[20:27], s[0:1], 0x20
	s_load_dwordx2 s[4:5], s[0:1], 0xb0
	s_mov_b32 s65, s52
	s_mov_b32 s52, s62
	s_mov_b32 s62, s54
	s_waitcnt lgkmcnt(0)
	s_cmp_lg_u64 s[20:21], 0
	s_cselect_b64 s[18:19], -1, 0
	s_add_u32 s28, s4, 0x800000
	s_addc_u32 s29, s5, 0
	v_readlane_b32 s14, v226, 0
	s_cmp_lg_u32 s14, 0
	s_cbranch_scc1 .Lgb_init_skip
	v_mov_b32_e32 v0, 0x25d6000
	v_mov_b32_e32 v1, 0
	global_store_dword v0, v1, s[4:5]
.Lgb_init_skip:
	s_mov_b32 s54, s51
	s_add_u32 s51, s4, 0x1300000
	s_addc_u32 s48, s5, 0
	s_load_dwordx4 s[36:39], s[0:1], 0x40
	s_load_dwordx2 s[34:35], s[0:1], 0x60
	s_cmp_lg_u64 s[24:25], 0
	s_cselect_b64 s[44:45], -1, 0
	s_add_u32 s84, s4, 0x14b0000
	s_movk_i32 s14, 0x180
	v_readlane_b32 s6, v226, 7
	s_addc_u32 s58, s5, 0
	s_waitcnt vmcnt(0)
	v_mul_lo_u32 v1, v8, s14
	v_readlane_b32 s14, v226, 0
	v_add_u32_e32 v0, s6, v8
	s_mov_b32 s6, 0x40000
	s_mov_b32 s8, 0x58000
	s_mov_b32 s10, 0xd800
	s_mov_b32 s12, 0xc000
	s_cmp_lg_u64 s[26:27], 0
	s_mul_i32 s14, s14, 0x30000
	v_cmp_gt_i32_e64 s[6:7], s6, v0
	v_cmp_gt_i32_e64 s[8:9], s8, v0
	v_cmp_gt_i32_e64 s[10:11], s10, v0
	v_cmp_gt_i32_e64 s[12:13], s12, v0
	s_cselect_b64 s[46:47], -1, 0
	v_add_u32_e32 v1, s14, v1
	s_mov_b32 s56, 0
	s_mov_b64 s[88:89], -1
	s_branch .LBB0_847

; __global__ void __launch_bounds__(512, 2) mega(Params p_, int ph_lo, int ph_hi, int coop) {
;     ...
;   for (int ph = ph_lo; ph < ph_hi; ph++) {
;     run_phase(p, ph, smem, 0);
;     if (coop && ph + 1 < ph_hi) cg::this_grid().sync();
.LBB0_1072:
	s_waitcnt vmcnt(0) lgkmcnt(0)
	s_barrier
	s_mov_b64 s[6:7], exec
	v_readlane_b32 s8, v226, 25
	v_readlane_b32 s9, v226, 26
	s_and_b64 s[8:9], s[6:7], s[8:9]
	s_mov_b64 exec, s[8:9]
	s_cbranch_execnz .LBB0_1073
	s_getpc_b64 s[98:99]

; __global__ void __launch_bounds__(512, 2) mega(Params p_, int ph_lo, int ph_hi, int coop) {
;     ...
;   for (int ph = ph_lo; ph < ph_hi; ph++) {
;     run_phase(p, ph, smem, 0);
;     if (coop && ph + 1 < ph_hi) cg::this_grid().sync();
.LBB0_1073:
	s_cmp_lt_u32 s12, 2
	s_cbranch_scc1 .Lgb_cg_path
	v_readlane_b32 s8, v226, 42
	v_readlane_b32 s9, v226, 43
	buffer_wbl2 sc1
	s_waitcnt vmcnt(0)
	s_load_dword s11, s[8:9], 0xc8
	s_load_dwordx2 s[8:9], s[8:9], 0xb0
	s_add_i32 s10, s12, -1
	v_mov_b32_e32 v1, 1
	s_waitcnt lgkmcnt(0)
	s_add_u32 s8, s8, 0x25d6000
	s_addc_u32 s9, s9, 0
	s_mul_i32 s10, s10, s11
	global_atomic_add v129, v1, s[8:9] sc1
	s_mov_b32 s11, 0
.Lgb_poll:
	s_sleep 1
	global_load_dword v1, v129, s[8:9] sc1
	s_add_u32 s11, s11, 1
	s_waitcnt vmcnt(0)
	v_cmp_gt_u32_e32 vcc, s10, v1
	s_and_b64 vcc, exec, vcc
	s_cbranch_vccz .Lgb_done
	s_cmp_lt_u32 s11, 0x20000
	s_cbranch_scc1 .Lgb_poll
.Lgb_done:
	buffer_inv sc1
	s_waitcnt vmcnt(0)
	s_branch .Lgb_to2

; __global__ void __launch_bounds__(512, 2) mega(Params p_, int ph_lo, int ph_hi, int coop) {
;     ...
;     if (coop && ph + 1 < ph_hi) cg::this_grid().sync();
.LBB0_1080:
	s_sleep 1
	global_load_dword v1, v129, s[8:9] offset:32 sc1
	s_waitcnt vmcnt(0)
	v_and_b32_e32 v1, 0xffff0000, v1
	v_cmp_ne_u32_e32 vcc, v1, v0
	s_or_b64 s[10:11], vcc, s[10:11]
	s_andn2_b64 exec, exec, s[10:11]
	s_cbranch_execnz .LBB0_1080
.Lgb_to2:
	s_getpc_b64 s[98:99]
